# FFN-out row-statistics exchange by polling pre-set (-1.0) slots instead of count-arrive, spin and reload
# speedup vs baseline: 1.0140x; 1.0010x over previous
.Lp4_entry:
	v_readlane_b32 s0, v252, 17
	v_mov_b32_e32 v4, 0xbf800000
	v_mov_b32_e32 v5, 0xbf800000
	v_or_b32_e32 v2, s0, v0
	v_lshlrev_b32_e32 v2, 3, v2
	global_store_dwordx2 v2, v[4:5], s[10:11]
	s_add_u32 s8, s80, 0x9a08800
	s_addc_u32 s9, s81, 0
	v_mov_b32_e32 v11, v0
	s_cmpk_lt_i32 s2, 0x1616
	s_nop 0
	v_readfirstlane_b32 s5, v11
	s_cbranch_scc0 .LBB0_613
	v_lshlrev_b32_e32 v1, 4, v11
	v_add_u32_e32 v2, 0x2000, v1
	v_ashrrev_i32_e32 v3, 31, v2
	v_lshrrev_b32_e32 v3, 22, v3
	v_add_u32_e32 v3, v2, v3
	v_ashrrev_i32_e32 v10, 10, v3
	v_mul_i32_i24_e32 v3, 0x400, v10
	v_sub_u32_e32 v2, v2, v3
	v_lshrrev_b32_e32 v3, 4, v2
	v_bitop3_b32 v2, v3, v2, 32 bitop3:0x6c
	v_ashrrev_i32_e32 v3, 31, v2
	v_lshrrev_b32_e32 v3, 26, v3
	v_add_u32_e32 v3, v2, v3
	v_lshlrev_b32_e32 v4, 3, v10
	v_ashrrev_i32_e32 v12, 6, v3
	v_and_b32_e32 v4, -16, v4
	v_add_u32_e32 v4, v12, v4
	v_and_b32_e32 v5, 3, v12
	s_mov_b32 s0, 0x1fffe0
	v_lshrrev_b32_e32 v6, 2, v4
	v_lshlrev_b32_e32 v7, 1, v4
	v_and_b32_e32 v3, 0xc0, v3
	v_and_or_b32 v5, v4, s0, v5
	v_and_b32_e32 v6, 4, v6
	v_and_b32_e32 v7, 24, v7
	v_sub_u32_e32 v2, v2, v3
	v_mov_b32_e32 v3, 1
	v_or3_b32 v5, v5, v6, v7
	v_lshlrev_b32_e32 v6, 5, v10
	v_ashrrev_i16_sdwa v2, v3, sext(v2) dst_sel:DWORD dst_unused:UNUSED_PAD src0_sel:DWORD src1_sel:BYTE_0
	v_and_b32_e32 v6, 32, v6
	v_bfe_i32 v13, v2, 0, 16
	v_add_lshl_u32 v2, v6, v13, 1
	v_lshl_add_u32 v130, v5, 11, v2
	s_waitcnt vmcnt(8)
	v_lshl_add_u32 v132, v4, 11, v2
	v_bfe_i32 v2, v11, 27, 1
	v_lshrrev_b32_e32 v2, 22, v2
	v_add_u32_e32 v2, v1, v2
	v_and_b32_e32 v2, 0xfffffc00, v2
	v_sub_u32_e32 v1, v1, v2
	v_lshrrev_b32_e32 v2, 4, v1
	v_ashrrev_i32_e32 v4, 31, v11
	v_bitop3_b32 v1, v2, v1, 32 bitop3:0x6c
	v_lshrrev_b32_e32 v4, 26, v4
	v_ashrrev_i32_e32 v2, 31, v1
	v_add_u32_e32 v4, v11, v4
	v_lshrrev_b32_e32 v2, 26, v2
	v_ashrrev_i32_e32 v15, 6, v4
	v_add_u32_e32 v2, v1, v2
	v_lshlrev_b32_e32 v4, 3, v15
	v_ashrrev_i32_e32 v14, 6, v2
	v_and_b32_e32 v4, -16, v4
	s_add_u32 s3, s80, 0x888800
	v_add_u32_e32 v4, v14, v4
	v_and_b32_e32 v5, 3, v14
	s_addc_u32 s17, s81, 0
	v_and_or_b32 v5, v4, s0, v5
	s_lshr_b32 s0, s86, 29
	s_add_i32 s0, s2, s0
	s_ashr_i32 s1, s0, 3
	s_and_b32 s0, s0, -8
	s_sub_i32 s0, s2, s0
	s_ashr_i32 s12, s5, 6
	s_mul_i32 s6, s0, 0x2c2
	s_ashr_i32 s14, s5, 8
	s_lshl_b32 s19, s12, 10
	s_add_i32 s6, s6, 6
	s_mul_i32 s4, s0, 0x2c3
	s_cmp_lt_i32 s0, 6
	s_cselect_b32 s0, s4, s6
	s_add_i32 s0, s0, s1
	s_mul_hi_i32 s1, s0, 0x2e8ba2e9
	s_lshr_b32 s4, s1, 31
	s_ashr_i32 s1, s1, 4
	v_lshrrev_b32_e32 v6, 2, v4
	v_lshlrev_b32_e32 v7, 1, v4
	v_and_b32_e32 v2, 0xc0, v2
	s_add_i32 s1, s1, s4
	v_and_b32_e32 v6, 4, v6
	v_and_b32_e32 v7, 24, v7
	v_sub_u32_e32 v1, v1, v2
	s_lshl_b32 s6, s1, 2
	v_or3_b32 v5, v5, v6, v7
	v_lshlrev_b32_e32 v6, 5, v15
	v_ashrrev_i16_sdwa v1, v3, sext(v1) dst_sel:DWORD dst_unused:UNUSED_PAD src0_sel:DWORD src1_sel:BYTE_0
	s_sub_i32 s4, 0x101, s6
	v_and_b32_e32 v6, 32, v6
	v_bfe_i32 v16, v1, 0, 16
	s_min_u32 s7, s4, 4
	s_mulk_i32 s1, 0x58
	v_add_lshl_u32 v1, v6, v16, 1
	s_sub_i32 s13, s0, s1
	v_cvt_f32_ubyte0_e32 v3, s7
	v_lshl_add_u32 v134, v5, 11, v1
	v_cvt_f32_i32_e32 v2, s13
	v_rcp_iflag_f32_e32 v5, v3
	v_lshl_add_u32 v136, v4, 11, v1
	s_ashr_i32 s0, s13, 30
	s_or_b32 s4, s0, 1
	v_mul_f32_e32 v1, v2, v5
	v_trunc_f32_e32 v1, v1
	v_fma_f32 v2, -v1, v3, v2
	v_cvt_i32_f32_e32 v1, v1
	v_cmp_ge_f32_e64 s[0:1], |v2|, v3
	s_and_b64 s[0:1], s[0:1], exec
	s_cselect_b32 s0, s4, 0
	v_readfirstlane_b32 s1, v1
	s_add_i32 s4, s1, s0
	s_mul_i32 s0, s4, s7
	s_sub_i32 s0, s13, s0
	s_sext_i32_i8 s0, s0
	s_add_i32 s0, s6, s0
	s_ashr_i32 s1, s0, 31
	s_bfe_i64 s[20:21], s[4:5], 0x80000
	s_lshl_b64 s[6:7], s[0:1], 19
	s_lshl_b64 s[20:21], s[20:21], 19
	s_add_u32 s30, s3, s20
	s_addc_u32 s31, s17, s21
	s_add_i32 s44, s19, 0
	s_add_i32 m0, s44, 0x10000
	v_mov_b32_e32 v135, 0
	global_load_lds_dwordx4 v134, s[30:31]
	s_add_i32 m0, s44, 0x12000
	s_add_u32 s20, s30, 0x40000
	global_load_lds_dwordx4 v130, s[30:31]
	s_addc_u32 s21, s31, 0
	s_add_i32 m0, s44, 0x14000
	v_mov_b32_e32 v131, v135
	global_load_lds_dwordx4 v134, s[20:21]
	s_add_i32 m0, s44, 0x16000
	s_add_u32 s28, s40, s6
	s_addc_u32 s29, s41, s7
	s_add_i32 s45, s44, 0x2000
	global_load_lds_dwordx4 v130, s[20:21]
	s_mov_b32 m0, s44
	s_add_u32 s6, s28, 0x40000
	global_load_lds_dwordx4 v136, s[28:29]
	s_mov_b32 m0, s45
	s_addc_u32 s7, s29, 0
	s_add_i32 s33, s44, 0x4000
	global_load_lds_dwordx4 v132, s[28:29]
	s_mov_b32 m0, s33
	s_add_i32 s46, s44, 0x6000
	global_load_lds_dwordx4 v136, s[6:7]
	s_mov_b32 m0, s46
	v_mov_b32_e32 v137, v135
	global_load_lds_dwordx4 v132, s[6:7]
	v_mov_b32_e32 v133, v135
	s_cmp_eq_u32 s14, 1
	s_mov_b32 s47, 0
	v_lshl_add_u64 v[8:9], s[30:31], 0, v[134:135]
	v_lshl_add_u64 v[6:7], s[30:31], 0, v[130:131]
	v_lshl_add_u64 v[2:3], s[28:29], 0, v[136:137]
	s_cselect_b64 s[6:7], -1, 0
	s_cmp_lg_u32 s14, 1
	v_lshl_add_u64 v[4:5], s[28:29], 0, v[132:133]
	s_cbranch_scc1 .LBB0_596
	s_barrier

.LBB0_721:
	s_or_b64 exec, exec, s[50:51]
	s_mov_b64 s[48:49], 0
	s_branch .LBB0_737

.LBB0_737:
	s_or_b64 exec, exec, s[48:49]
	v_mov_b32_e32 v189, v171
	v_mov_b32_e32 v187, v171
	v_mov_b32_e32 v185, v171
	v_mov_b32_e32 v161, v171
	v_mov_b32_e32 v159, v171
	v_mov_b32_e32 v157, v171
	v_mov_b32_e32 v155, v171
	v_mov_b32_e32 v205, v171
	v_mov_b32_e32 v203, v171
	v_mov_b32_e32 v201, v171
	v_mov_b32_e32 v199, v171
	v_mov_b32_e32 v197, v171
	v_mov_b32_e32 v195, v171
	v_mov_b32_e32 v193, v171
	v_mov_b32_e32 v191, v171
	s_waitcnt lgkmcnt(0)
	v_lshl_add_u64 v[130:131], s[40:41], 0, v[170:171]
	v_lshl_add_u64 v[132:133], s[40:41], 0, v[188:189]
	v_lshl_add_u64 v[134:135], s[40:41], 0, v[186:187]
	v_lshl_add_u64 v[146:147], s[40:41], 0, v[184:185]
	v_lshl_add_u64 v[148:149], s[40:41], 0, v[160:161]
	v_lshl_add_u64 v[152:153], s[40:41], 0, v[158:159]
	v_lshl_add_u64 v[150:151], s[40:41], 0, v[156:157]
	v_lshl_add_u64 v[206:207], s[40:41], 0, v[154:155]
	v_lshl_add_u64 v[184:185], s[40:41], 0, v[204:205]
	v_lshl_add_u64 v[186:187], s[40:41], 0, v[202:203]
	v_lshl_add_u64 v[188:189], s[40:41], 0, v[200:201]
	v_lshl_add_u64 v[198:199], s[40:41], 0, v[198:199]
	v_lshl_add_u64 v[196:197], s[40:41], 0, v[196:197]
	v_lshl_add_u64 v[194:195], s[40:41], 0, v[194:195]
	v_lshl_add_u64 v[192:193], s[40:41], 0, v[192:193]
	v_lshl_add_u64 v[190:191], s[40:41], 0, v[190:191]
	s_barrier
	s_and_saveexec_b64 s[48:49], s[34:35]
	s_cbranch_execz .LBB0_739
	s_ashr_i32 s47, s46, 31
	s_lshl_b64 s[36:37], s[46:47], 12
	v_lshl_add_u64 v[136:137], v[172:173], 0, s[36:37]
	s_mov_b32 s33, 0
.Lxch_spin:
	global_load_dword v138, v[136:137], off sc1
	global_load_dword v140, v[136:137], off offset:4 sc1
	global_load_dword v139, v[136:137], off offset:8 sc1
	global_load_dword v141, v[136:137], off offset:12 sc1
	s_waitcnt vmcnt(0)
	v_or3_b32 v142, v138, v139, v140
	v_or_b32_e32 v142, v142, v141
	v_cmp_gt_i32_e32 vcc, 0, v142
	s_cbranch_vccz .Lxch_done
	s_add_u32 s33, s33, 1
	s_cmp_lt_u32 s33, 0x80000
	s_cbranch_scc0 .Lxch_done
	s_sleep 1
	s_branch .Lxch_spin
.Lxch_done:
	v_pk_add_f32 v[136:137], v[138:139], v[140:141]
	s_nop 0
	v_add_f32_e32 v136, v136, v137
	v_fmamk_f32 v136, v136, 0x3a800000, v216
	v_mul_f32_e32 v137, 0x4b800000, v136
	v_cmp_gt_f32_e32 vcc, s69, v136
	s_nop 1
	v_cndmask_b32_e32 v136, v136, v137, vcc
	v_rsq_f32_e32 v136, v136
	s_nop 0
	v_mul_f32_e32 v137, 0x45800000, v136
	v_cndmask_b32_e32 v136, v136, v137, vcc
	ds_write_b32 v217, v136 offset:4096
